# combo8 + grid barrier: cache invalidate issued right after arrival (overlaps the wait) instead of after release; assumption: no data loads on the CU between arrival and release
# speedup vs baseline: 1.0038x; 1.0038x over previous
.LBB0_516:
	s_or_b64 exec, exec, s[10:11]
	v_cvt_f32_u32_e32 v5, v3
	s_waitcnt vmcnt(0)
	v_readfirstlane_b32 s8, v4
	v_sub_u32_e32 v4, 0, v3
	v_rcp_iflag_f32_e32 v5, v5
	v_add_u32_e32 v6, s8, v2
	v_mul_f32_e32 v5, 0x4f7ffffe, v5
	v_cvt_u32_f32_e32 v5, v5
	v_mul_lo_u32 v2, v4, v5
	v_mul_hi_u32 v2, v5, v2
	v_add_u32_e32 v2, v5, v2
	v_mul_hi_u32 v2, v6, v2
	v_mul_lo_u32 v4, v2, v3
	v_sub_u32_e32 v4, v6, v4
	v_add_u32_e32 v5, 1, v2
	v_cmp_ge_u32_e32 vcc, v4, v3
	s_nop 1
	v_cndmask_b32_e32 v2, v2, v5, vcc
	v_sub_u32_e32 v5, v4, v3
	v_cndmask_b32_e32 v4, v4, v5, vcc
	v_add_u32_e32 v5, 1, v2
	v_cmp_ge_u32_e32 vcc, v4, v3
	v_add_u32_e32 v4, 1, v6
	s_nop 0
	v_cndmask_b32_e32 v2, v2, v5, vcc
	v_mul_lo_u32 v5, v3, v2
	v_add_u32_e32 v3, v5, v3
	v_cmp_ne_u32_e32 vcc, v4, v3
	s_and_saveexec_b64 s[8:9], vcc
	s_xor_b64 s[8:9], exec, s[8:9]
	s_cbranch_execz .LBB0_530
	buffer_inv sc1
	s_waitcnt lgkmcnt(0)
	v_mov_b32_e32 v0, 0x2000
	global_load_dword v0, v0, s[6:7] offset:1024 sc1
	s_add_u32 s14, s6, 0x2400
	s_addc_u32 s15, s7, 0
	s_waitcnt vmcnt(0)
	v_cmp_eq_u32_e32 vcc, v0, v2
	s_and_saveexec_b64 s[10:11], vcc
	s_cbranch_execz .LBB0_529
	s_add_u32 s12, s78, 0x10200
	s_addc_u32 s13, s79, 0
	s_mov_b32 s26, 1
	s_mov_b64 s[16:17], 0
	s_branch .LBB0_520

.LBB0_529:
	s_or_b64 exec, exec, s[10:11]
	s_waitcnt vmcnt(0)
	s_waitcnt vmcnt(0)
.LBB0_530:
	s_andn2_saveexec_b64 s[8:9], s[8:9]
	s_cbranch_execz .LBB0_4
	s_mov_b64 s[8:9], exec
	buffer_wbl2 sc1
	s_waitcnt lgkmcnt(0)
	s_waitcnt vmcnt(0)
	buffer_inv sc1
	v_mbcnt_lo_u32_b32 v2, s8, 0
	v_mbcnt_hi_u32_b32 v2, s9, v2
	v_cmp_eq_u32_e32 vcc, 0, v2
	s_and_saveexec_b64 s[10:11], vcc
	s_cbranch_execz .LBB0_533
	s_bcnt1_i32_b64 s8, s[8:9]
	v_mov_b32_e32 v3, s8
	v_mov_b32_e32 v4, 0x13000
	global_atomic_add v3, v4, v3, s[78:79] offset:1024 sc0

.LBB0_547:
	s_or_b64 exec, exec, s[8:9]
	s_mov_b64 s[8:9], exec
	v_mbcnt_lo_u32_b32 v0, s8, 0
	v_mbcnt_hi_u32_b32 v0, s9, v0
	v_cmp_eq_u32_e32 vcc, 0, v0
	s_waitcnt vmcnt(0)
	s_and_saveexec_b64 s[10:11], vcc
	s_cbranch_execz .LBB0_3
	s_bcnt1_i32_b64 s8, s[8:9]
	v_mov_b32_e32 v0, s8
	v_mov_b32_e32 v2, 0x2000
	global_atomic_add v2, v0, s[6:7] offset:1024
	s_branch .LBB0_3
